# attention: V transpose-reads hoisted above softmax and PV MFMAs (hide LDS latency)
# speedup vs baseline: 1.0023x; 1.0023x over previous
; #define SBAR() __builtin_amdgcn_sched_barrier(0)
; __device__ __forceinline__ s16x4 vtr(lds_cptr p) { return __builtin_bit_cast(s16x4, __builtin_amdgcn_ds_read_tr16_b64_v4i16((__attribute__((address_space(3))) v4i16_t*)p)); }
; __device__ __forceinline__ void finishSM(f32x16& p0, f32x16& p1, float alpha, float& l_reg, bf16x8& pa0, bf16x8& pa1, bf16x8& pa2, bf16x8& pa3) {
; #pragma unroll
;   for (int r = 0; r < 16; ++r) p1[r] = __builtin_amdgcn_exp2f(p1[r]);
;   float ps = 0;
; #pragma unroll
;   for (int r = 0; r < 16; ++r) ps += p0[r];
; #pragma unroll
;   for (int r = 0; r < 16; ++r) ps += p1[r];
;   { auto rr = __builtin_amdgcn_permlane32_swap(__float_as_uint(ps), __float_as_uint(ps), false, false);
;     ps = __uint_as_float(rr[0]) + __uint_as_float(rr[1]); }
;   l_reg = l_reg * alpha + ps;
;     ...
;   PK4(p0, 0, pa0); PK4(p0, 8, pa1); PK4(p1, 0, pa2); PK4(p1, 8, pa3);
;     ...
; }
; template <int KS> __device__ __forceinline__ void v_read(VFrag& f, lds_cptr vp) {
; #pragma unroll
;   for (int d0 = 0; d0 < 4; ++d0) { f.lo[d0] = vtr(vp + v_rd_off(d0, KS, 0)); f.hi[d0] = vtr(vp + v_rd_off(d0, KS, 1)); }
; }
; __device__ __forceinline__ void pv_slice(f32x16* o, const VFrag& f, bf16x8 pa) {
; #pragma unroll
;   for (int d0 = 0; d0 < 4; ++d0) { const bf16x8 vf = (bf16x8){f.lo[d0][0], f.lo[d0][1], f.lo[d0][2], f.lo[d0][3], f.hi[d0][0], f.hi[d0][1], f.hi[d0][2], f.hi[d0][3]};
;     o[d0] = __builtin_amdgcn_mfma_f32_32x32x16_bf16(pa, vf, o[d0], 0, 0, 0); }
; }
; __device__ __forceinline__ void pv_all(f32x16* o, lds_cptr vp, bf16x8 pa0, bf16x8 pa1, bf16x8 pa2, bf16x8 pa3) {
;   VFrag fa, fb;
;   v_read<0>(fa, vp); v_read<1>(fb, vp); SBAR();
;   pv_slice(o, fa, pa0); SBAR(); v_read<2>(fa, vp); SBAR();
;   pv_slice(o, fb, pa1); SBAR(); v_read<3>(fb, vp); SBAR();
;   pv_slice(o, fa, pa2); SBAR();
;   pv_slice(o, fb, pa3); SBAR();
; }
.LBB0_320:
	v_add_u32_e32 v244, s59, v170
	ds_read_b64_tr_b16 v[232:233], v244 offset:16384
	ds_read_b64_tr_b16 v[236:237], v244 offset:16896
	ds_read_b64_tr_b16 v[240:241], v244 offset:17408
	ds_read_b64_tr_b16 v[198:199], v244 offset:17920
	ds_read_b64_tr_b16 v[234:235], v244 offset:18432
	ds_read_b64_tr_b16 v[238:239], v244 offset:18944
	ds_read_b64_tr_b16 v[242:243], v244 offset:19456
	ds_read_b64_tr_b16 v[200:201], v244 offset:19968
	ds_read_b64_tr_b16 v[202:203], v244 offset:20480
	ds_read_b64_tr_b16 v[206:207], v244 offset:20992
	ds_read_b64_tr_b16 v[210:211], v244 offset:21504
	ds_read_b64_tr_b16 v[214:215], v244 offset:22016
	ds_read_b64_tr_b16 v[204:205], v244 offset:22528
	ds_read_b64_tr_b16 v[208:209], v244 offset:23040
	ds_read_b64_tr_b16 v[212:213], v244 offset:23552
	ds_read_b64_tr_b16 v[216:217], v244 offset:24064
	s_nop 1
	v_exp_f32_e32 v179, v80
	v_exp_f32_e32 v180, v81
	v_exp_f32_e32 v181, v82
	v_exp_f32_e32 v83, v83
	v_exp_f32_e32 v84, v84
	v_add_f32_e32 v80, 0, v179
	v_exp_f32_e32 v85, v85
	v_add_f32_e32 v80, v180, v80
	v_exp_f32_e32 v86, v86
	v_add_f32_e32 v80, v181, v80
	v_exp_f32_e32 v87, v87
	v_add_f32_e32 v80, v83, v80
	v_exp_f32_e32 v88, v88
	v_add_f32_e32 v80, v84, v80
	v_exp_f32_e32 v89, v89
	v_add_f32_e32 v80, v85, v80
	v_exp_f32_e32 v90, v90
	v_add_f32_e32 v80, v86, v80
	v_exp_f32_e32 v91, v91
	v_add_f32_e32 v80, v87, v80
	v_exp_f32_e32 v92, v92
	v_add_f32_e32 v80, v88, v80
	v_exp_f32_e32 v93, v93
	v_add_f32_e32 v80, v89, v80
	v_exp_f32_e32 v94, v94
	v_add_f32_e32 v80, v90, v80
	v_exp_f32_e32 v95, v95
	v_add_f32_e32 v80, v91, v80
	v_exp_f32_e32 v96, v96
	v_add_f32_e32 v80, v92, v80
	v_exp_f32_e32 v97, v97
	v_add_f32_e32 v80, v93, v80
	v_exp_f32_e32 v98, v98
	v_add_f32_e32 v80, v94, v80
	v_exp_f32_e32 v99, v99
	v_add_f32_e32 v80, v95, v80
	v_exp_f32_e32 v100, v100
	v_add_f32_e32 v80, v96, v80
	v_exp_f32_e32 v101, v101
	v_add_f32_e32 v80, v97, v80
	v_exp_f32_e32 v102, v102
	v_add_f32_e32 v80, v98, v80
	v_exp_f32_e32 v103, v103
	v_add_f32_e32 v80, v99, v80
	v_exp_f32_e32 v104, v104
	v_add_f32_e32 v80, v100, v80
	v_exp_f32_e32 v105, v105
	v_add_f32_e32 v80, v101, v80
	v_exp_f32_e32 v106, v106
	v_add_f32_e32 v80, v102, v80
	v_exp_f32_e32 v107, v107
	v_add_f32_e32 v80, v103, v80
	v_exp_f32_e32 v108, v108
	v_add_f32_e32 v80, v104, v80
	v_exp_f32_e32 v109, v109
	v_add_f32_e32 v80, v105, v80
	v_exp_f32_e32 v110, v110
	v_add_f32_e32 v80, v106, v80
	v_exp_f32_e32 v111, v111
	v_add_f32_e32 v80, v107, v80
	v_add_f32_e32 v80, v108, v80
	v_add_f32_e32 v80, v109, v80
	v_add_f32_e32 v80, v110, v80
	v_add_f32_e32 v80, v111, v80
	v_mov_b32_e32 v81, v80
	s_nop 1
	v_permlane32_swap_b32_e32 v80, v81
	v_cvt_pk_bf16_f32 v82, v179, v180
	v_cvt_pk_bf16_f32 v83, v181, v83
	v_cvt_pk_bf16_f32 v84, v84, v85
	v_cvt_pk_bf16_f32 v85, v86, v87
	v_cvt_pk_bf16_f32 v86, v88, v89
	v_cvt_pk_bf16_f32 v87, v90, v91
	v_cvt_pk_bf16_f32 v88, v92, v93
	v_cvt_pk_bf16_f32 v89, v94, v95
	v_cvt_pk_bf16_f32 v90, v96, v97
	v_cvt_pk_bf16_f32 v91, v98, v99
	v_cvt_pk_bf16_f32 v92, v100, v101
	v_cvt_pk_bf16_f32 v93, v102, v103
	v_cvt_pk_bf16_f32 v94, v104, v105
	v_cvt_pk_bf16_f32 v95, v106, v107
	v_cvt_pk_bf16_f32 v96, v108, v109
	v_cvt_pk_bf16_f32 v97, v110, v111
	s_nop 0
	v_permlane32_swap_b32_e32 v82, v84
	v_permlane32_swap_b32_e32 v83, v85
	v_permlane32_swap_b32_e32 v86, v88
	v_permlane32_swap_b32_e32 v87, v89
	v_permlane32_swap_b32_e32 v90, v92
	v_permlane32_swap_b32_e32 v91, v93
	v_permlane32_swap_b32_e32 v94, v96
	v_permlane32_swap_b32_e32 v95, v97
	ds_read_b64_tr_b16 v[246:247], v244 offset:24576
	ds_read_b64_tr_b16 v[98:99], v244 offset:25088
	ds_read_b64_tr_b16 v[102:103], v244 offset:25600
	ds_read_b64_tr_b16 v[106:107], v244 offset:26112
	ds_read_b64_tr_b16 v[248:249], v244 offset:26624
	ds_read_b64_tr_b16 v[100:101], v244 offset:27136
	ds_read_b64_tr_b16 v[104:105], v244 offset:27648
	ds_read_b64_tr_b16 v[108:109], v244 offset:28160
	s_waitcnt lgkmcnt(8)
	v_mfma_f32_32x32x16_bf16 v[0:15], v[82:85], v[232:235], v[0:15]
	v_mfma_f32_32x32x16_bf16 v[16:31], v[82:85], v[236:239], v[16:31]
	v_mfma_f32_32x32x16_bf16 v[32:47], v[82:85], v[240:243], v[32:47]
	v_mfma_f32_32x32x16_bf16 v[48:63], v[82:85], v[198:201], v[48:63]
	v_mfma_f32_32x32x16_bf16 v[0:15], v[86:89], v[202:205], v[0:15]
	v_mfma_f32_32x32x16_bf16 v[16:31], v[86:89], v[206:209], v[16:31]
	v_mfma_f32_32x32x16_bf16 v[32:47], v[86:89], v[210:213], v[32:47]
	v_mfma_f32_32x32x16_bf16 v[48:63], v[86:89], v[214:217], v[48:63]
	ds_read_b64_tr_b16 v[86:87], v244 offset:28672
	ds_read_b64_tr_b16 v[198:199], v244 offset:29184
	ds_read_b64_tr_b16 v[202:203], v244 offset:29696
	ds_read_b64_tr_b16 v[206:207], v244 offset:30208
	ds_read_b64_tr_b16 v[88:89], v244 offset:30720
	ds_read_b64_tr_b16 v[200:201], v244 offset:31232
	ds_read_b64_tr_b16 v[204:205], v244 offset:31744
	ds_read_b64_tr_b16 v[208:209], v244 offset:32256
	s_waitcnt lgkmcnt(8)
	v_mfma_f32_32x32x16_bf16 v[0:15], v[90:93], v[246:249], v[0:15]
	v_mfma_f32_32x32x16_bf16 v[16:31], v[90:93], v[98:101], v[16:31]
	v_mfma_f32_32x32x16_bf16 v[32:47], v[90:93], v[102:105], v[32:47]
	v_mfma_f32_32x32x16_bf16 v[48:63], v[90:93], v[106:109], v[48:63]
	s_waitcnt lgkmcnt(0)
	v_mfma_f32_32x32x16_bf16 v[0:15], v[94:97], v[86:89], v[0:15]
	v_mfma_f32_32x32x16_bf16 v[16:31], v[94:97], v[198:201], v[16:31]
	v_mfma_f32_32x32x16_bf16 v[32:47], v[94:97], v[202:205], v[32:47]
	v_mfma_f32_32x32x16_bf16 v[48:63], v[94:97], v[206:209], v[48:63]
	s_mov_b64 s[8:9], -1
	s_and_b64 vcc, exec, s[6:7]
	s_cbranch_vccz .LBB0_322
	s_waitcnt vmcnt(0) lgkmcnt(0)
	s_barrier
	s_mov_b64 s[8:9], 0
